# attention row sums as v_pk_add_f32 on same-row register pairs, 39 adds per tile pair instead of 60 (v17 base, no K hoist)
# baseline (speedup 1.0000x reference)
.LBB0_961:
	s_waitcnt vmcnt(5)
	s_barrier
	s_mov_b32 s19, s5
	s_mov_b32 s5, s25
	s_mul_i32 s9, s25, 0x6000
	s_add_i32 s25, s9, 0
	v_add_u32_e32 v124, s25, v225
	ds_read_b128 v[120:123], v124
	ds_read_b128 v[160:163], v124 offset:4096
	ds_read_b128 v[168:171], v124 offset:8192
	ds_read_b128 v[172:175], v124 offset:12288
	v_exp_f32_e32 v188, v148
	v_exp_f32_e32 v189, v149
	v_exp_f32_e32 v194, v150
	v_exp_f32_e32 v195, v151
	s_waitcnt lgkmcnt(3)
	v_mfma_f32_16x16x32_bf16 v[124:127], v[120:123], v[4:7], v[48:51]
	v_mfma_f32_16x16x32_bf16 v[120:123], v[120:123], v[40:43], v[52:55]
	v_add_u32_e32 v196, s25, v234
	ds_read_b128 v[184:187], v196
	s_waitcnt lgkmcnt(3)
	v_mfma_f32_16x16x32_bf16 v[148:151], v[160:163], v[4:7], v[48:51]
	v_mfma_f32_16x16x32_bf16 v[160:163], v[160:163], v[40:43], v[52:55]
	ds_read_b128 v[176:179], v196 offset:4096
	s_waitcnt lgkmcnt(3)
	v_mfma_f32_16x16x32_bf16 v[164:167], v[168:171], v[4:7], v[48:51]
	v_exp_f32_e32 v190, v140
	v_exp_f32_e32 v191, v141
	v_mfma_f32_16x16x32_bf16 v[168:171], v[168:171], v[40:43], v[52:55]
	ds_read_b128 v[180:183], v196 offset:8192
	v_exp_f32_e32 v192, v142
	v_exp_f32_e32 v193, v143
	s_waitcnt lgkmcnt(3)
	v_mfma_f32_16x16x32_bf16 v[140:143], v[172:175], v[4:7], v[48:51]
	v_pk_add_f32 v[198:199], v[156:157], v[158:159]
	v_pk_add_f32 v[214:215], v[144:145], v[146:147]
	v_mfma_f32_16x16x32_bf16 v[172:175], v[172:175], v[40:43], v[52:55]
	s_add_i32 s9, s4, -1
	s_cmp_ge_u32 s9, s2
	s_cbranch_scc1 .LBB0_963
	s_add_u32 s9, s6, s30
	s_addc_u32 s35, s7, s31
	s_add_u32 s34, s9, 0x180000
	s_addc_u32 s35, s35, 0
	s_add_u32 s36, s10, 0xffffe000
	s_mul_i32 s9, s8, 0x6000
	s_addc_u32 s37, s11, -1
	s_add_i32 s9, s9, 0
	s_add_i32 s48, s9, s77
	s_mov_b32 m0, s48
	s_add_i32 s9, s9, s97
	global_load_lds_dwordx4 v227, s[34:35]
	s_add_i32 m0, s48, 0x400
	s_nop 0
	global_load_lds_dwordx4 v229, s[34:35]
	s_add_i32 m0, s9, 0x4000
	s_nop 0
	global_load_lds_dwordx4 v232, s[36:37]
.LBB0_963:
	s_add_u32 s36, s28, s30
	s_addc_u32 s37, s29, s31
	s_add_u32 s34, s36, 0x100000
	s_addc_u32 s35, s37, 0
	s_lshl_b32 s9, s19, 14
	s_add_i32 s48, s95, s9
	s_mov_b32 m0, s48
	s_nop 0
	global_load_lds_dwordx4 v228, s[34:35]
	s_add_i32 m0, s48, 0x400
	s_nop 0
	global_load_lds_dwordx4 v231, s[34:35]
	ds_read_b128 v[236:239], v196 offset:12288
	s_waitcnt lgkmcnt(3)
	v_mfma_f32_16x16x32_bf16 v[120:123], v[184:187], v[36:39], v[120:123]
	v_exp_f32_e32 v196, v132
	v_exp_f32_e32 v208, v133
	v_mfma_f32_16x16x32_bf16 v[124:127], v[184:187], v[0:3], v[124:127]
	v_add_u32_e32 v209, s25, v233
	ds_read_b128 v[184:187], v209
	v_exp_f32_e32 v210, v134
	v_exp_f32_e32 v211, v135
	s_waitcnt lgkmcnt(3)
	v_mfma_f32_16x16x32_bf16 v[132:135], v[176:179], v[0:3], v[148:151]
	v_mfma_f32_16x16x32_bf16 v[160:163], v[176:179], v[36:39], v[160:163]
	s_nop 1
	v_pk_add_f32 v[198:199], v[198:199], v[152:153]
	v_pk_add_f32 v[214:215], v[214:215], v[136:137]
	ds_read_b128 v[176:179], v209 offset:4096
	s_waitcnt lgkmcnt(3)
	v_mfma_f32_16x16x32_bf16 v[164:167], v[180:183], v[0:3], v[164:167]
	v_exp_f32_e32 v212, v128
	v_exp_f32_e32 v213, v129
	v_mfma_f32_16x16x32_bf16 v[168:171], v[180:183], v[36:39], v[168:171]
	ds_read_b128 v[180:183], v209 offset:8192
	v_exp_f32_e32 v219, v130
	v_exp_f32_e32 v235, v131
	s_waitcnt lgkmcnt(3)
	v_mfma_f32_16x16x32_bf16 v[128:131], v[236:239], v[0:3], v[140:143]
	v_pk_add_f32 v[198:199], v[198:199], v[154:155]
	v_pk_add_f32 v[214:215], v[214:215], v[138:139]
	v_mfma_f32_16x16x32_bf16 v[140:143], v[236:239], v[36:39], v[172:175]
	s_nop 2
	ds_read_b128 v[172:175], v209 offset:12288
	s_waitcnt lgkmcnt(3)
	v_mfma_f32_16x16x32_bf16 v[120:123], v[184:187], v[28:31], v[120:123]
	v_mfma_f32_16x16x32_bf16 v[124:127], v[184:187], v[12:15], v[124:127]
	v_cvt_pk_bf16_f32 v148, v156, v157
	v_add_u32_e32 v206, s25, v230
	ds_read_b128 v[184:187], v206
	v_pk_add_f32 v[198:199], v[198:199], v[188:189]
	v_pk_add_f32 v[214:215], v[214:215], v[190:191]
	s_waitcnt lgkmcnt(3)
	v_mfma_f32_16x16x32_bf16 v[132:135], v[176:179], v[12:15], v[132:135]
	v_cvt_pk_bf16_f32 v149, v158, v159
	v_mfma_f32_16x16x32_bf16 v[156:159], v[176:179], v[28:31], v[160:163]
	ds_read_b128 v[176:179], v206 offset:4096
	s_waitcnt lgkmcnt(3)
	v_mfma_f32_16x16x32_bf16 v[162:165], v[180:183], v[12:15], v[164:167]
	s_nop 0
	v_mfma_f32_16x16x32_bf16 v[166:169], v[180:183], v[28:31], v[168:171]
	v_cvt_pk_bf16_f32 v150, v152, v153
	ds_read_b128 v[180:183], v206 offset:8192
	s_waitcnt lgkmcnt(3)
	v_mfma_f32_16x16x32_bf16 v[128:131], v[172:175], v[12:15], v[128:131]
	v_pk_add_f32 v[198:199], v[198:199], v[194:195]
	v_pk_add_f32 v[214:215], v[214:215], v[192:193]
	v_mfma_f32_16x16x32_bf16 v[140:143], v[172:175], v[28:31], v[140:143]
	v_cvt_pk_bf16_f32 v151, v154, v155
	ds_read_b128 v[152:155], v206 offset:12288
	s_waitcnt lgkmcnt(3)
	v_mfma_f32_16x16x32_bf16 v[120:123], v[184:187], v[24:27], v[120:123]
	v_add_f32_e32 v198, v196, v198
	v_mfma_f32_16x16x32_bf16 v[124:127], v[184:187], v[8:11], v[124:127]
	v_cvt_pk_bf16_f32 v160, v144, v145
	v_add_u32_e32 v186, s25, v226
	ds_read_b128 v[170:173], v186 offset:16384
	v_add_f32_e32 v199, v208, v199
	v_pk_add_f32 v[214:215], v[214:215], v[212:213]
	s_waitcnt lgkmcnt(3)
	v_mfma_f32_16x16x32_bf16 v[132:135], v[176:179], v[8:11], v[132:135]
	v_cvt_pk_bf16_f32 v161, v146, v147
	v_mfma_f32_16x16x32_bf16 v[144:147], v[176:179], v[24:27], v[156:159]
	s_nop 2
	ds_read_b128 v[156:159], v186 offset:18432
	s_waitcnt lgkmcnt(3)
	v_mfma_f32_16x16x32_bf16 v[174:177], v[180:183], v[8:11], v[162:165]
	v_mfma_f32_16x16x32_bf16 v[178:181], v[180:183], v[24:27], v[166:169]
	s_nop 1
	v_add_f32_e32 v214, v219, v214
	v_cvt_pk_bf16_f32 v162, v136, v137
	ds_read_b128 v[182:185], v186 offset:20480
	v_pk_add_f32 v[198:199], v[198:199], v[210:211]
	v_add_f32_e32 v206, v198, v199
	v_add_f32_e32 v215, v235, v215
	v_add_f32_e32 v207, v214, v215
	s_waitcnt lgkmcnt(3)
	v_mfma_f32_16x16x32_bf16 v[128:131], v[152:155], v[8:11], v[128:131]
	v_cvt_pk_bf16_f32 v163, v138, v139
	v_mfma_f32_16x16x32_bf16 v[136:139], v[152:155], v[24:27], v[140:143]
	s_nop 2
	ds_read_b128 v[140:143], v186 offset:22528
	s_waitcnt lgkmcnt(3)
	v_mfma_f32_16x16x32_bf16 v[120:123], v[170:173], v[32:35], v[120:123]
	v_cvt_pk_bf16_f32 v164, v188, v189
	v_mfma_f32_16x16x32_bf16 v[124:127], v[170:173], v[16:19], v[124:127]
	v_add_u32_e32 v152, s25, v224
	ds_read_b128 v[168:171], v152 offset:16384
	s_waitcnt lgkmcnt(3)
	v_mfma_f32_16x16x32_bf16 v[132:135], v[156:159], v[16:19], v[132:135]
	v_cvt_pk_bf16_f32 v165, v194, v195
	v_mfma_f32_16x16x32_bf16 v[186:189], v[156:159], v[32:35], v[144:147]
	ds_read_b128 v[236:239], v152 offset:18432
	s_waitcnt lgkmcnt(3)
	v_mfma_f32_16x16x32_bf16 v[240:243], v[182:185], v[16:19], v[174:177]
	v_cvt_pk_bf16_f32 v166, v196, v208
	v_mfma_f32_16x16x32_bf16 v[176:179], v[182:185], v[32:35], v[178:181]
	s_nop 2
	ds_read_b128 v[180:183], v152 offset:20480
	s_waitcnt lgkmcnt(3)
	v_mfma_f32_16x16x32_bf16 v[128:131], v[140:143], v[16:19], v[128:131]
	v_cvt_pk_bf16_f32 v167, v210, v211
	v_mfma_f32_16x16x32_bf16 v[244:247], v[140:143], v[32:35], v[136:139]
	ds_read_b128 v[248:251], v152 offset:22528
	s_waitcnt lgkmcnt(3)
	v_mfma_f32_16x16x32_bf16 v[152:155], v[168:171], v[20:23], v[124:127]
	v_mfma_f32_16x16x32_bf16 v[144:147], v[168:171], v[44:47], v[120:123]
	v_cvt_pk_bf16_f32 v168, v190, v191
	s_waitcnt lgkmcnt(2)
	v_mfma_f32_16x16x32_bf16 v[156:159], v[236:239], v[20:23], v[132:135]
	v_cvt_pk_bf16_f32 v169, v192, v193
	v_mfma_f32_16x16x32_bf16 v[172:175], v[236:239], v[44:47], v[186:189]
	s_waitcnt lgkmcnt(1)
	v_mfma_f32_16x16x32_bf16 v[140:143], v[180:183], v[20:23], v[240:243]
	v_cvt_pk_bf16_f32 v170, v212, v213
	v_mfma_f32_16x16x32_bf16 v[136:139], v[180:183], v[44:47], v[176:179]
	s_waitcnt lgkmcnt(0)
	v_mfma_f32_16x16x32_bf16 v[132:135], v[248:251], v[20:23], v[128:131]
	v_cvt_pk_bf16_f32 v171, v219, v235
	v_mfma_f32_16x16x32_bf16 v[128:131], v[248:251], v[44:47], v[244:247]
	s_lshl_b32 s34, s8, 14
	s_add_i32 s48, s34, 0
	s_add_i32 s48, s48, 0x12000
	v_add_u32_e32 v196, s48, v222
	v_add_u32_e32 v219, s48, v223
	ds_read_b64_tr_b16 v[176:177], v219
	ds_read_b64_tr_b16 v[178:179], v219 offset:4096
	ds_read_b64_tr_b16 v[184:185], v219 offset:8192
	ds_read_b64_tr_b16 v[186:187], v219 offset:12288
	ds_read_b64_tr_b16 v[120:121], v196
	ds_read_b64_tr_b16 v[122:123], v196 offset:4096
	ds_read_b64_tr_b16 v[124:125], v196 offset:8192
	ds_read_b64_tr_b16 v[126:127], v196 offset:12288
	ds_read_b64_tr_b16 v[182:183], v219 offset:4608
	ds_read_b64_tr_b16 v[180:181], v219 offset:512
	ds_read_b64_tr_b16 v[190:191], v219 offset:12800
	ds_read_b64_tr_b16 v[188:189], v219 offset:8704
	s_waitcnt lgkmcnt(10)
	v_mfma_f32_16x16x32_bf16 v[112:115], v[176:179], v[148:151], v[112:115]
	v_mfma_f32_16x16x32_bf16 v[116:119], v[176:179], v[160:163], v[116:119]
	v_max_f32_e32 v176, v152, v153
	s_waitcnt lgkmcnt(8)
	v_mfma_f32_16x16x32_bf16 v[112:115], v[184:187], v[164:167], v[112:115]
	v_max3_f32 v176, v176, v154, v155
	v_max3_f32 v176, v176, v156, v157
	v_max3_f32 v208, v176, v158, v159
	v_mfma_f32_16x16x32_bf16 v[116:119], v[184:187], v[168:171], v[116:119]
	ds_read_b64_tr_b16 v[192:193], v196 offset:512
	ds_read_b64_tr_b16 v[194:195], v196 offset:4608
	ds_read_b64_tr_b16 v[236:237], v196 offset:8704
	ds_read_b64_tr_b16 v[238:239], v196 offset:12800
	s_waitcnt lgkmcnt(10)
	v_mfma_f32_16x16x32_bf16 v[108:111], v[120:123], v[148:151], v[108:111]
	v_mfma_f32_16x16x32_bf16 v[176:179], v[120:123], v[160:163], v[104:107]
	s_waitcnt lgkmcnt(8)
	v_mfma_f32_16x16x32_bf16 v[104:107], v[124:127], v[164:167], v[108:111]
	s_nop 5
	v_max3_f32 v108, v208, v140, v141
	v_max3_f32 v108, v108, v142, v143
	v_max3_f32 v108, v108, v132, v133
	v_max3_f32 v120, v108, v134, v135
	v_mfma_f32_16x16x32_bf16 v[108:111], v[124:127], v[168:171], v[176:179]
	ds_read_b64_tr_b16 v[184:185], v219 offset:1024
	ds_read_b64_tr_b16 v[186:187], v219 offset:5120
	s_nop 0
	ds_read_b64_tr_b16 v[176:177], v219 offset:9216
	ds_read_b64_tr_b16 v[178:179], v219 offset:13312
	s_waitcnt lgkmcnt(10)
	v_mfma_f32_16x16x32_bf16 v[96:99], v[180:183], v[148:151], v[96:99]
	v_max_f32_e32 v121, v144, v145
	s_waitcnt lgkmcnt(8)
	v_mfma_f32_16x16x32_bf16 v[96:99], v[188:191], v[164:167], v[96:99]
	v_max3_f32 v121, v121, v146, v147
	v_max3_f32 v121, v121, v172, v173
	v_max3_f32 v121, v121, v174, v175
	v_mfma_f32_16x16x32_bf16 v[100:103], v[180:183], v[160:163], v[100:103]
	v_mfma_f32_16x16x32_bf16 v[100:103], v[188:191], v[168:171], v[100:103]
	ds_read_b64_tr_b16 v[188:189], v196 offset:1024
	ds_read_b64_tr_b16 v[190:191], v196 offset:5120
	ds_read_b64_tr_b16 v[180:181], v196 offset:9216
	ds_read_b64_tr_b16 v[182:183], v196 offset:13312
	s_waitcnt lgkmcnt(10)
	v_mfma_f32_16x16x32_bf16 v[92:95], v[192:195], v[148:151], v[92:95]
	v_mfma_f32_16x16x32_bf16 v[122:125], v[192:195], v[160:163], v[88:91]
	s_waitcnt lgkmcnt(8)
	v_mfma_f32_16x16x32_bf16 v[88:91], v[236:239], v[164:167], v[92:95]
	s_nop 5
	v_max3_f32 v92, v121, v136, v137
	v_max3_f32 v92, v92, v138, v139
	v_max3_f32 v92, v92, v128, v129
	v_max3_f32 v121, v92, v130, v131
	v_mfma_f32_16x16x32_bf16 v[92:95], v[236:239], v[168:171], v[122:125]
	s_nop 2
	v_max_f32_e32 v122, v120, v121
	v_cmp_ge_f32_e32 vcc, s62, v122
	s_cmp_lg_u64 vcc, exec
	s_cselect_b64 s[34:35], -1, 0
	s_cmp_eq_u64 vcc, exec
	s_cbranch_scc1 .LBB0_965
	ds_bpermute_b32 v48, v220, v120
	v_max_f32_e32 v49, v120, v120
	v_max_f32_e32 v50, v121, v121
	s_waitcnt lgkmcnt(0)
	v_max_f32_e32 v48, v48, v48
	v_max_f32_e32 v48, v49, v48
	ds_bpermute_b32 v49, v221, v48
	s_waitcnt lgkmcnt(0)
	v_max3_f32 v48, v48, v49, 0
	ds_bpermute_b32 v49, v220, v121
	v_exp_f32_e64 v208, -v48
	v_sub_f32_e32 v152, v152, v48
	v_sub_f32_e32 v153, v153, v48
	v_sub_f32_e32 v154, v154, v48
	s_waitcnt lgkmcnt(0)
	v_max_f32_e32 v49, v49, v49
	v_max_f32_e32 v49, v50, v49
	ds_bpermute_b32 v50, v221, v49
	v_sub_f32_e32 v155, v155, v48
	v_sub_f32_e32 v156, v156, v48
	v_sub_f32_e32 v157, v157, v48
	v_sub_f32_e32 v158, v158, v48
	s_waitcnt lgkmcnt(0)
	v_max3_f32 v49, v49, v50, 0
	v_exp_f32_e64 v209, -v49
	v_pk_add_f32 v[202:203], v[202:203], v[48:49]
	v_sub_f32_e32 v159, v159, v48
	v_pk_add_f32 v[120:121], v[202:203], 0 neg_lo:[1,1] neg_hi:[1,1]
	v_xor_b32_e32 v124, 0x80000000, v203
	v_sub_f32_e32 v143, v143, v48
	v_sub_f32_e32 v142, v142, v48
	v_sub_f32_e32 v141, v141, v48
	v_sub_f32_e32 v140, v140, v48
	v_sub_f32_e32 v135, v135, v48
	v_sub_f32_e32 v134, v134, v48
	v_sub_f32_e32 v133, v133, v48
	v_sub_f32_e32 v132, v132, v48
	v_mov_b32_e32 v121, v120
	v_mov_b32_e32 v122, v120
	v_mov_b32_e32 v123, v120
	v_sub_f32_e32 v144, v144, v49
	v_sub_f32_e32 v145, v145, v49
	v_sub_f32_e32 v146, v146, v49
	v_sub_f32_e32 v147, v147, v49
	v_sub_f32_e32 v172, v172, v49
	v_sub_f32_e32 v173, v173, v49
	v_sub_f32_e32 v174, v174, v49
	v_sub_f32_e32 v175, v175, v49
	v_sub_f32_e32 v139, v139, v49
	v_sub_f32_e32 v138, v138, v49
	v_sub_f32_e32 v137, v137, v49
	v_sub_f32_e32 v136, v136, v49
	v_sub_f32_e32 v131, v131, v49
	v_sub_f32_e32 v130, v130, v49
	v_sub_f32_e32 v129, v129, v49
	v_sub_f32_e32 v128, v128, v49
	v_mov_b32_e32 v125, v124
	v_mov_b32_e32 v126, v124
	v_mov_b32_e32 v127, v124
	v_mov_b32_e32 v48, v120
	v_mov_b32_e32 v49, v120
	v_mov_b32_e32 v50, v120
	v_mov_b32_e32 v51, v120
	v_mov_b32_e32 v52, v124
	v_mov_b32_e32 v53, v124
	v_mov_b32_e32 v54, v124
	v_mov_b32_e32 v55, v124
	s_branch .LBB0_966

.LBB0_969:
	s_waitcnt vmcnt(5)
	s_barrier
	s_mul_i32 s34, s19, 0x6000
	s_add_i32 s49, s34, 0
	v_add_u32_e32 v164, s49, v225
	ds_read_b128 v[160:163], v164
	ds_read_b128 v[168:171], v164 offset:4096
	ds_read_b128 v[184:187], v164 offset:8192
	ds_read_b128 v[246:249], v164 offset:12288
	v_exp_f32_e32 v235, v140
	v_exp_f32_e32 v236, v141
	v_exp_f32_e32 v241, v142
	v_exp_f32_e32 v242, v143
	s_waitcnt lgkmcnt(3)
	v_mfma_f32_16x16x32_bf16 v[164:167], v[160:163], v[4:7], v[120:123]
	v_mfma_f32_16x16x32_bf16 v[160:163], v[160:163], v[40:43], v[124:127]
	v_add_u32_e32 v243, s49, v234
	ds_read_b128 v[192:195], v243
	s_waitcnt lgkmcnt(3)
	v_mfma_f32_16x16x32_bf16 v[180:183], v[168:171], v[4:7], v[120:123]
	v_mfma_f32_16x16x32_bf16 v[172:175], v[168:171], v[40:43], v[124:127]
	ds_read_b128 v[188:191], v243 offset:4096
	v_exp_f32_e32 v237, v136
	v_exp_f32_e32 v238, v137
	s_waitcnt lgkmcnt(3)
	v_mfma_f32_16x16x32_bf16 v[176:179], v[184:187], v[4:7], v[120:123]
	v_mfma_f32_16x16x32_bf16 v[140:143], v[184:187], v[40:43], v[124:127]
	ds_read_b128 v[184:187], v243 offset:8192
	v_exp_f32_e32 v239, v138
	v_exp_f32_e32 v240, v139
	s_waitcnt lgkmcnt(3)
	v_mfma_f32_16x16x32_bf16 v[168:171], v[246:249], v[4:7], v[120:123]
	v_pk_add_f32 v[212:213], v[152:153], v[154:155]
	v_pk_add_f32 v[244:245], v[144:145], v[146:147]
	v_mfma_f32_16x16x32_bf16 v[136:139], v[246:249], v[40:43], v[124:127]
	s_cmp_ge_u32 s4, s2
	s_cselect_b64 s[34:35], -1, 0
	s_and_b64 vcc, exec, s[34:35]
	s_cbranch_vccnz .LBB0_971
	s_add_u32 s65, s6, s30
	s_addc_u32 s69, s7, s31
	s_add_u32 s70, s65, 0x200000
	s_addc_u32 s71, s69, 0
	s_add_i32 s65, s25, s77
	s_mov_b64 s[80:81], s[10:11]
	s_mov_b32 m0, s65
	s_add_i32 s25, s25, s97
	global_load_lds_dwordx4 v227, s[70:71]
	s_add_i32 m0, s65, 0x400
	s_nop 0
	global_load_lds_dwordx4 v229, s[70:71]
	s_add_i32 m0, s25, 0x4000
	s_nop 0
	global_load_lds_dwordx4 v232, s[80:81]
.LBB0_971:
	s_add_u32 s36, s36, 0x180000
	s_addc_u32 s37, s37, 0
	s_add_i32 s25, s48, s77
	s_mov_b32 m0, s25
	s_nop 0
	global_load_lds_dwordx4 v228, s[36:37]
	s_add_i32 m0, s25, 0x400
	s_nop 0
	global_load_lds_dwordx4 v231, s[36:37]
	ds_read_b128 v[246:249], v243 offset:12288
	s_waitcnt lgkmcnt(3)
	v_mfma_f32_16x16x32_bf16 v[164:167], v[192:195], v[0:3], v[164:167]
	v_exp_f32_e32 v210, v132
	v_exp_f32_e32 v211, v133
	v_mfma_f32_16x16x32_bf16 v[160:163], v[192:195], v[36:39], v[160:163]
	v_add_u32_e32 v243, s49, v233
	ds_read_b128 v[192:195], v243
	v_exp_f32_e32 v250, v134
	v_exp_f32_e32 v251, v135
	s_waitcnt lgkmcnt(3)
	v_mfma_f32_16x16x32_bf16 v[132:135], v[188:191], v[0:3], v[180:183]
	v_pk_add_f32 v[212:213], v[212:213], v[156:157]
	v_pk_add_f32 v[244:245], v[244:245], v[148:149]
	v_mfma_f32_16x16x32_bf16 v[172:175], v[188:191], v[36:39], v[172:175]
	ds_read_b128 v[180:183], v243 offset:4096
	s_waitcnt lgkmcnt(3)
	v_mfma_f32_16x16x32_bf16 v[176:179], v[184:187], v[0:3], v[176:179]
	v_exp_f32_e32 v215, v128
	v_exp_f32_e32 v214, v129
	v_mfma_f32_16x16x32_bf16 v[140:143], v[184:187], v[36:39], v[140:143]
	ds_read_b128 v[184:187], v243 offset:8192
	v_exp_f32_e32 v218, v130
	v_exp_f32_e32 v198, v131
	s_waitcnt lgkmcnt(3)
	v_mfma_f32_16x16x32_bf16 v[128:131], v[246:249], v[0:3], v[168:171]
	v_pk_add_f32 v[212:213], v[212:213], v[158:159]
	v_pk_add_f32 v[244:245], v[244:245], v[150:151]
	v_mfma_f32_16x16x32_bf16 v[168:171], v[246:249], v[36:39], v[136:139]
	ds_read_b128 v[188:191], v243 offset:12288
	s_waitcnt lgkmcnt(3)
	v_mfma_f32_16x16x32_bf16 v[164:167], v[192:195], v[12:15], v[164:167]
	v_add_f32_e32 v212, v235, v212
	v_add_f32_e32 v244, v237, v244
	v_mfma_f32_16x16x32_bf16 v[160:163], v[192:195], v[28:31], v[160:163]
	v_cvt_pk_bf16_f32 v136, v152, v153
	v_add_u32_e32 v199, s49, v230
	ds_read_b128 v[192:195], v199
	v_add_f32_e32 v213, v236, v213
	v_add_f32_e32 v245, v238, v245
	s_waitcnt lgkmcnt(3)
	v_mfma_f32_16x16x32_bf16 v[132:135], v[180:183], v[12:15], v[132:135]
	v_cvt_pk_bf16_f32 v137, v154, v155
	v_mfma_f32_16x16x32_bf16 v[152:155], v[180:183], v[28:31], v[172:175]
	s_nop 2
	ds_read_b128 v[172:175], v199 offset:4096
	s_waitcnt lgkmcnt(3)
	v_mfma_f32_16x16x32_bf16 v[176:179], v[184:187], v[12:15], v[176:179]
	v_add_f32_e32 v212, v241, v212
	v_add_f32_e32 v244, v239, v244
	v_mfma_f32_16x16x32_bf16 v[140:143], v[184:187], v[28:31], v[140:143]
	v_cvt_pk_bf16_f32 v138, v156, v157
	ds_read_b128 v[180:183], v199 offset:8192
	v_add_f32_e32 v213, v242, v213
	v_add_f32_e32 v245, v240, v245
	s_waitcnt lgkmcnt(3)
	v_mfma_f32_16x16x32_bf16 v[128:131], v[188:191], v[12:15], v[128:131]
	v_cvt_pk_bf16_f32 v139, v158, v159
	v_mfma_f32_16x16x32_bf16 v[156:159], v[188:191], v[28:31], v[168:171]
	s_nop 2
	ds_read_b128 v[168:171], v199 offset:12288
	s_waitcnt lgkmcnt(3)
	v_mfma_f32_16x16x32_bf16 v[164:167], v[192:195], v[8:11], v[164:167]
	v_mfma_f32_16x16x32_bf16 v[184:187], v[192:195], v[24:27], v[160:163]
	s_nop 2
	v_cvt_pk_bf16_f32 v160, v144, v145
	v_add_u32_e32 v192, s49, v226
	ds_read_b128 v[188:191], v192 offset:16384
	v_pk_add_f32 v[212:213], v[212:213], v[210:211]
	v_pk_add_f32 v[244:245], v[244:245], v[214:215]
	s_waitcnt lgkmcnt(3)
	v_mfma_f32_16x16x32_bf16 v[132:135], v[172:175], v[8:11], v[132:135]
	v_cvt_pk_bf16_f32 v161, v146, v147
	v_mfma_f32_16x16x32_bf16 v[144:147], v[172:175], v[24:27], v[152:155]
	s_nop 2
	ds_read_b128 v[152:155], v192 offset:18432
	s_waitcnt lgkmcnt(3)
	v_mfma_f32_16x16x32_bf16 v[172:175], v[180:183], v[8:11], v[176:179]
	v_add_f32_e32 v244, v218, v244
	v_mfma_f32_16x16x32_bf16 v[140:143], v[180:183], v[24:27], v[140:143]
	v_cvt_pk_bf16_f32 v162, v148, v149
	ds_read_b128 v[176:179], v192 offset:20480
	v_pk_add_f32 v[212:213], v[212:213], v[250:251]
	v_add_f32_e32 v194, v212, v213
	v_add_f32_e32 v245, v198, v245
	v_add_f32_e32 v195, v244, v245
	s_waitcnt lgkmcnt(3)
	v_mfma_f32_16x16x32_bf16 v[128:131], v[168:171], v[8:11], v[128:131]
	v_cvt_pk_bf16_f32 v163, v150, v151
	v_mfma_f32_16x16x32_bf16 v[148:151], v[168:171], v[24:27], v[156:159]
	s_nop 2
	ds_read_b128 v[156:159], v192 offset:22528
	s_waitcnt lgkmcnt(3)
	v_mfma_f32_16x16x32_bf16 v[168:171], v[188:191], v[16:19], v[164:167]
	v_cvt_pk_bf16_f32 v164, v235, v236
	v_mfma_f32_16x16x32_bf16 v[180:183], v[188:191], v[32:35], v[184:187]
	v_add_u32_e32 v192, s49, v224
	s_nop 1
	ds_read_b128 v[184:187], v192 offset:16384
	s_waitcnt lgkmcnt(3)
	v_mfma_f32_16x16x32_bf16 v[132:135], v[152:155], v[16:19], v[132:135]
	v_cvt_pk_bf16_f32 v165, v241, v242
	v_mfma_f32_16x16x32_bf16 v[188:191], v[152:155], v[32:35], v[144:147]
	ds_read_b128 v[242:245], v192 offset:18432
	s_waitcnt lgkmcnt(3)
	v_mfma_f32_16x16x32_bf16 v[140:143], v[176:179], v[32:35], v[140:143]
	v_cvt_pk_bf16_f32 v166, v210, v211
	v_mfma_f32_16x16x32_bf16 v[246:249], v[176:179], v[16:19], v[172:175]
	ds_read_b128 v[176:179], v192 offset:20480
	s_waitcnt lgkmcnt(3)
	v_mfma_f32_16x16x32_bf16 v[128:131], v[156:159], v[16:19], v[128:131]
	v_cvt_pk_bf16_f32 v167, v250, v251
	v_mfma_f32_16x16x32_bf16 v[250:253], v[156:159], v[32:35], v[148:151]
	ds_read_b128 v[210:213], v192 offset:22528
	s_waitcnt lgkmcnt(3)
	v_mfma_f32_16x16x32_bf16 v[156:159], v[184:187], v[20:23], v[168:171]
	v_cvt_pk_bf16_f32 v168, v237, v238
	v_mfma_f32_16x16x32_bf16 v[144:147], v[184:187], v[44:47], v[180:183]
	s_waitcnt lgkmcnt(2)
	v_mfma_f32_16x16x32_bf16 v[152:155], v[242:245], v[20:23], v[132:135]
	v_cvt_pk_bf16_f32 v169, v239, v240
	v_mfma_f32_16x16x32_bf16 v[172:175], v[242:245], v[44:47], v[188:191]
	s_waitcnt lgkmcnt(1)
	v_mfma_f32_16x16x32_bf16 v[148:151], v[176:179], v[20:23], v[246:249]
	v_cvt_pk_bf16_f32 v170, v215, v214
	v_mfma_f32_16x16x32_bf16 v[140:143], v[176:179], v[44:47], v[140:143]
	s_waitcnt lgkmcnt(0)
	v_mfma_f32_16x16x32_bf16 v[132:135], v[210:213], v[20:23], v[128:131]
	v_cvt_pk_bf16_f32 v171, v218, v198
	v_mfma_f32_16x16x32_bf16 v[128:131], v[210:213], v[44:47], v[250:253]
	s_lshl_b32 s25, s5, 14
	s_add_i32 s25, s25, 0
	s_add_i32 s25, s25, 0x12000
	v_add_u32_e32 v235, s25, v222
	v_add_u32_e32 v236, s25, v223
	ds_read_b64_tr_b16 v[184:185], v236
	ds_read_b64_tr_b16 v[186:187], v236 offset:4096
	ds_read_b64_tr_b16 v[210:211], v236 offset:8192
	ds_read_b64_tr_b16 v[212:213], v236 offset:12288
	ds_read_b64_tr_b16 v[176:177], v235
	ds_read_b64_tr_b16 v[178:179], v235 offset:4096
	ds_read_b64_tr_b16 v[180:181], v235 offset:8192
	ds_read_b64_tr_b16 v[182:183], v235 offset:12288
	ds_read_b64_tr_b16 v[190:191], v236 offset:4608
	ds_read_b64_tr_b16 v[188:189], v236 offset:512
	ds_read_b64_tr_b16 v[240:241], v236 offset:12800
	ds_read_b64_tr_b16 v[238:239], v236 offset:8704
	s_waitcnt lgkmcnt(10)
	v_mfma_f32_16x16x32_bf16 v[112:115], v[184:187], v[136:139], v[112:115]
	v_mfma_f32_16x16x32_bf16 v[116:119], v[184:187], v[160:163], v[116:119]
	v_max_f32_e32 v184, v156, v157
	s_waitcnt lgkmcnt(8)
	v_mfma_f32_16x16x32_bf16 v[112:115], v[210:213], v[164:167], v[112:115]
	v_max3_f32 v184, v184, v158, v159
	v_max3_f32 v184, v184, v152, v153
	v_max3_f32 v184, v184, v154, v155
	v_mfma_f32_16x16x32_bf16 v[116:119], v[210:213], v[168:171], v[116:119]
	ds_read_b64_tr_b16 v[210:211], v235 offset:512
	ds_read_b64_tr_b16 v[212:213], v235 offset:4608
	ds_read_b64_tr_b16 v[242:243], v235 offset:8704
	ds_read_b64_tr_b16 v[244:245], v235 offset:12800
	s_waitcnt lgkmcnt(10)
	v_mfma_f32_16x16x32_bf16 v[104:107], v[176:179], v[136:139], v[104:107]
	v_mfma_f32_16x16x32_bf16 v[176:179], v[176:179], v[160:163], v[108:111]
	s_waitcnt lgkmcnt(8)
	v_mfma_f32_16x16x32_bf16 v[108:111], v[180:183], v[164:167], v[104:107]
	s_nop 5
	v_max3_f32 v104, v184, v148, v149
	v_max3_f32 v104, v104, v150, v151
	v_max3_f32 v104, v104, v132, v133
	v_max3_f32 v193, v104, v134, v135
	v_mfma_f32_16x16x32_bf16 v[104:107], v[180:183], v[168:171], v[176:179]
	ds_read_b64_tr_b16 v[184:185], v236 offset:1024
	ds_read_b64_tr_b16 v[186:187], v236 offset:5120
	s_nop 0
	ds_read_b64_tr_b16 v[176:177], v236 offset:9216
	ds_read_b64_tr_b16 v[178:179], v236 offset:13312
	s_waitcnt lgkmcnt(10)
	v_mfma_f32_16x16x32_bf16 v[96:99], v[188:191], v[136:139], v[96:99]
	v_max_f32_e32 v180, v144, v145
	s_waitcnt lgkmcnt(8)
	v_mfma_f32_16x16x32_bf16 v[96:99], v[238:241], v[164:167], v[96:99]
	v_max3_f32 v180, v180, v146, v147
	v_max3_f32 v180, v180, v172, v173
	v_max3_f32 v192, v180, v174, v175
	v_mfma_f32_16x16x32_bf16 v[100:103], v[188:191], v[160:163], v[100:103]
	v_mfma_f32_16x16x32_bf16 v[100:103], v[238:241], v[168:171], v[100:103]
	ds_read_b64_tr_b16 v[188:189], v235 offset:1024
	ds_read_b64_tr_b16 v[190:191], v235 offset:5120
	ds_read_b64_tr_b16 v[180:181], v235 offset:9216
	ds_read_b64_tr_b16 v[182:183], v235 offset:13312
	s_waitcnt lgkmcnt(10)
	v_mfma_f32_16x16x32_bf16 v[88:91], v[210:213], v[136:139], v[88:91]
	v_mfma_f32_16x16x32_bf16 v[210:213], v[210:213], v[160:163], v[92:95]
	s_waitcnt lgkmcnt(8)
	v_mfma_f32_16x16x32_bf16 v[92:95], v[242:245], v[164:167], v[88:91]
	s_nop 5
	v_max3_f32 v88, v192, v140, v141
	v_max3_f32 v88, v88, v142, v143
	v_max3_f32 v88, v88, v128, v129
	v_max3_f32 v237, v88, v130, v131
	v_mfma_f32_16x16x32_bf16 v[88:91], v[242:245], v[168:171], v[210:213]
	v_max_f32_e32 v192, v193, v237
	v_cmp_ge_f32_e32 vcc, s62, v192
	s_cmp_lg_u64 vcc, exec
	s_cselect_b64 s[36:37], -1, 0
	s_cmp_eq_u64 vcc, exec
	v_mov_b32_e32 v192, 1.0
	s_cbranch_scc1 .LBB0_973
	ds_bpermute_b32 v48, v220, v193
	v_max_f32_e32 v49, v193, v193
	v_max_f32_e32 v50, v237, v237
	s_waitcnt lgkmcnt(0)
	v_max_f32_e32 v48, v48, v48
	v_max_f32_e32 v48, v49, v48
	ds_bpermute_b32 v49, v221, v48
	s_waitcnt lgkmcnt(0)
	v_max3_f32 v48, v48, v49, 0
	ds_bpermute_b32 v49, v220, v237
	v_exp_f32_e64 v192, -v48
	v_sub_f32_e32 v156, v156, v48
	v_sub_f32_e32 v157, v157, v48
	v_sub_f32_e32 v158, v158, v48
	s_waitcnt lgkmcnt(0)
	v_max_f32_e32 v49, v49, v49
	v_max_f32_e32 v49, v50, v49
	ds_bpermute_b32 v50, v221, v49
	v_sub_f32_e32 v159, v159, v48
	v_sub_f32_e32 v152, v152, v48
	v_sub_f32_e32 v153, v153, v48
	v_sub_f32_e32 v154, v154, v48
	s_waitcnt lgkmcnt(0)
	v_max3_f32 v49, v49, v50, 0
	v_exp_f32_e64 v193, -v49
	v_pk_add_f32 v[202:203], v[202:203], v[48:49]
	v_sub_f32_e32 v155, v155, v48
	v_pk_add_f32 v[120:121], v[202:203], 0 neg_lo:[1,1] neg_hi:[1,1]
	v_xor_b32_e32 v124, 0x80000000, v203
	v_sub_f32_e32 v151, v151, v48
	v_sub_f32_e32 v150, v150, v48
	v_sub_f32_e32 v149, v149, v48
	v_sub_f32_e32 v148, v148, v48
	v_sub_f32_e32 v135, v135, v48
	v_sub_f32_e32 v134, v134, v48
	v_sub_f32_e32 v133, v133, v48
	v_sub_f32_e32 v132, v132, v48
	v_mov_b32_e32 v121, v120
	v_mov_b32_e32 v122, v120
	v_mov_b32_e32 v123, v120
	v_sub_f32_e32 v144, v144, v49
	v_sub_f32_e32 v145, v145, v49
	v_sub_f32_e32 v146, v146, v49
	v_sub_f32_e32 v147, v147, v49
	v_sub_f32_e32 v172, v172, v49
	v_sub_f32_e32 v173, v173, v49
	v_sub_f32_e32 v174, v174, v49
	v_sub_f32_e32 v175, v175, v49
	v_sub_f32_e32 v143, v143, v49
	v_sub_f32_e32 v142, v142, v49
	v_sub_f32_e32 v141, v141, v49
	v_sub_f32_e32 v140, v140, v49
	v_sub_f32_e32 v131, v131, v49
	v_sub_f32_e32 v130, v130, v49
	v_sub_f32_e32 v129, v129, v49
	v_sub_f32_e32 v128, v128, v49
	v_mov_b32_e32 v125, v124
	v_mov_b32_e32 v126, v124
	v_mov_b32_e32 v127, v124
	v_mov_b32_e32 v48, v120
	v_mov_b32_e32 v49, v120
	v_mov_b32_e32 v50, v120
	v_mov_b32_e32 v51, v120
	v_mov_b32_e32 v52, v124
	v_mov_b32_e32 v53, v124
	v_mov_b32_e32 v54, v124
	v_mov_b32_e32 v55, v124
	s_branch .LBB0_974
